# P0/P4 weight transposition: 32 row loads in flight plus next-item prefetch instead of 8 loads and 4 round trips per item
# speedup vs baseline: 1.0021x; 1.0021x over previous
; #define GAS __attribute__((address_space(1)))
; #define LAS __attribute__((address_space(3)))
; #define LDS_WAIT() asm volatile("s_waitcnt lgkmcnt(0)" ::: "memory")
; __device__ __forceinline__ unsigned pk2(float lo, float hi) { return f2bf(lo) | (f2bf(hi) << 16); }
; __device__ __forceinline__ void p0_transpose_item(const float* W, int K, int N, bf16* WT, LAS float* scr, int item, int lane) {
;     const int nblk = N / 32, kb = item / nblk, nb = item % nblk, k0 = 64 * kb, n0 = 32 * nb;
; #pragma unroll 8
;     for (int i = 0; i < 32; ++i) { const int kk = 2 * i + (lane >> 5); scr[kk * 33 + (lane & 31)] = __builtin_nontemporal_load(W + (size_t)(k0 + kk) * N + n0 + (lane & 31)); }
;     LDS_WAIT(); asm volatile("" ::: "memory");
;     const int c = lane & 7;
; #pragma unroll
;     for (int j = 0; j < 4; ++j) { const int n = (lane >> 3) + 8 * j; const LAS float* s = scr + (8 * c) * 33 + n;
;         v4u o; o.x = pk2(s[0 * 33], s[1 * 33]); o.y = pk2(s[2 * 33], s[3 * 33]); o.z = pk2(s[4 * 33], s[5 * 33]); o.w = pk2(s[6 * 33], s[7 * 33]);
;         *(GAS v4u*)(WT + (size_t)(n0 + n) * K + k0 + 8 * c) = o; }
;     LDS_WAIT(); asm volatile("" ::: "memory");
; }
; __device__ __forceinline__ void transpose_all(const Frame& F, const float* W, int K, int N, bf16* WT) {
;     LAS float* scr = (LAS float*)(F.lds + F.wave * 16384);
;     const int gw = F.vcu * NWAVES + F.wave, NGW = F.G * NWAVES, nitems = (K / 64) * (N / 32);
;     for (int it = gw; it < nitems; it += NGW) p0_transpose_item(W, K, N, WT, scr, it, F.lane);
; __global__ void __launch_bounds__(NWAVES * 64, 2) mega(Args args) {
;     ...
;         transpose_all(F, args.in[2], D, INC, (bf16*)(ws + WS_WIN));
;         transpose_all(F, args.in[10], D, D, (bf16*)(ws + WS_WPA));
;         transpose_all(F, args.in[11], D, D, (bf16*)(ws + WS_WPL));
;         transpose_all(F, args.in[12], D, D, (bf16*)(ws + WS_WOUT));
;         transpose_all(F, args.in[14], D, FF, (bf16*)(ws + WS_WUP));
.LBB0_30:
	s_or_b64 exec, exec, s[2:3]
	s_lshl_b32 s8, s92, 14
	v_lshrrev_b32_e32 v36, 5, v156
	v_and_b32_e32 v37, 31, v156
	v_lshlrev_b32_e32 v37, 2, v37
	s_movk_i32 s7, 0x84
	v_mad_u32_u24 v33, v36, s7, v37
	v_add_u32_e32 v33, s8, v33
	v_and_b32_e32 v38, 7, v156
	v_lshrrev_b32_e32 v39, 3, v156
	s_movk_i32 s7, 0x420
	v_lshlrev_b32_e32 v34, 2, v39
	v_mad_u32_u24 v34, v38, s7, v34
	v_add_u32_e32 v34, s8, v34
	v_lshlrev_b32_e32 v35, 12, v39
	v_lshl_add_u32 v35, v38, 4, v35
	v_readlane_b32 s36, v234, 9
	v_readlane_b32 s37, v234, 10
	v_readlane_b32 s38, v234, 25
	v_readlane_b32 s39, v234, 26
	v_readlane_b32 s40, v234, 27
	v_readlane_b32 s41, v234, 28
	v_readlane_b32 s42, v234, 29
	v_readlane_b32 s43, v234, 30
	v_readlane_b32 s44, v234, 33
	v_readlane_b32 s45, v234, 34
	s_mov_b32 s46, -1
	s_mov_b32 s47, 0
	s_mov_b32 s49, 0
	s_mov_b32 s13, 0
	s_nop 3
.Ltr_next:
	s_add_u32 s47, s47, s78
.Ltr_chk:
	s_cmp_lt_u32 s47, s49
	s_cbranch_scc1 .Ltr_have
	s_add_u32 s46, s46, 1
	s_cmp_ge_u32 s46, 5
	s_cbranch_scc1 .Ltr_none
	s_mov_b32 s47, s74
	s_mov_b32 s48, 0x2000
	s_movk_i32 s49, 0x800
	s_mov_b64 s[50:51], s[36:37]
	s_lshl_b32 s10, s46, 23
	s_cmp_eq_u32 s46, 0
	s_cselect_b32 s48, 0xe000, s48
	s_cselect_b32 s49, 0x3800, s49
	s_cselect_b32 s10, 0x2000000, s10
	s_cmp_eq_u32 s46, 1
	s_cselect_b64 s[50:51], s[38:39], s[50:51]
	s_cmp_eq_u32 s46, 2
	s_cselect_b64 s[50:51], s[40:41], s[50:51]
	s_cmp_eq_u32 s46, 3
	s_cselect_b64 s[50:51], s[42:43], s[50:51]
	s_cmp_eq_u32 s46, 4
	s_cselect_b64 s[50:51], s[44:45], s[50:51]
	s_cselect_b32 s48, 0x8000, s48
	s_cselect_b32 s49, 0x2000, s49
	s_cselect_b32 s10, 0x1e000000, s10
	s_add_u32 s10, s88, s10
	s_addc_u32 s11, s89, 0
	v_mad_u32_u24 v32, v36, s48, v37
	s_branch .Ltr_chk
.Ltr_have:
	s_cmp_eq_u32 s46, 0
	s_cbranch_scc0 .Ltr_pow2
	s_lshr_b32 s7, s47, 6
	s_mul_hi_u32 s7, s7, 0x24924925
	s_mul_i32 s12, s7, 0x1c0
	s_sub_u32 s12, s47, s12
	s_branch .Ltr_dec
.Ltr_pow2:
	s_mov_b32 s0, 6
	s_cmp_eq_u32 s46, 4
	s_cselect_b32 s0, 8, s0
	s_lshr_b32 s7, s47, s0
	s_lshl_b32 s12, s7, s0
	s_sub_u32 s12, s47, s12
.Ltr_dec:
	s_lshl_b32 s6, s12, 17
	s_lshl_b32 s0, s7, 7
	s_add_u32 s6, s6, s0
	s_add_u32 s2, s10, s6
	s_addc_u32 s3, s11, 0
	s_lshl_b32 s0, s7, 6
	s_mul_i32 s0, s0, s48
	s_lshl_b32 s1, s12, 7
	s_add_u32 s0, s0, s1
	s_add_u32 s0, s50, s0
	s_addc_u32 s1, s51, 0
	s_lshl_b32 s6, s48, 1
	global_load_dword v0, v32, s[0:1] nt
	s_add_u32 s0, s0, s6
	s_addc_u32 s1, s1, 0
	global_load_dword v1, v32, s[0:1] nt
	s_add_u32 s0, s0, s6
	s_addc_u32 s1, s1, 0
	global_load_dword v2, v32, s[0:1] nt
	s_add_u32 s0, s0, s6
	s_addc_u32 s1, s1, 0
	global_load_dword v3, v32, s[0:1] nt
	s_add_u32 s0, s0, s6
	s_addc_u32 s1, s1, 0
	global_load_dword v4, v32, s[0:1] nt
	s_add_u32 s0, s0, s6
	s_addc_u32 s1, s1, 0
	global_load_dword v5, v32, s[0:1] nt
	s_add_u32 s0, s0, s6
	s_addc_u32 s1, s1, 0
	global_load_dword v6, v32, s[0:1] nt
	s_add_u32 s0, s0, s6
	s_addc_u32 s1, s1, 0
	global_load_dword v7, v32, s[0:1] nt
	s_add_u32 s0, s0, s6
	s_addc_u32 s1, s1, 0
	global_load_dword v8, v32, s[0:1] nt
	s_add_u32 s0, s0, s6
	s_addc_u32 s1, s1, 0
	global_load_dword v9, v32, s[0:1] nt
	s_add_u32 s0, s0, s6
	s_addc_u32 s1, s1, 0
	global_load_dword v10, v32, s[0:1] nt
	s_add_u32 s0, s0, s6
	s_addc_u32 s1, s1, 0
	global_load_dword v11, v32, s[0:1] nt
	s_add_u32 s0, s0, s6
	s_addc_u32 s1, s1, 0
	global_load_dword v12, v32, s[0:1] nt
	s_add_u32 s0, s0, s6
	s_addc_u32 s1, s1, 0
	global_load_dword v13, v32, s[0:1] nt
	s_add_u32 s0, s0, s6
	s_addc_u32 s1, s1, 0
	global_load_dword v14, v32, s[0:1] nt
	s_add_u32 s0, s0, s6
	s_addc_u32 s1, s1, 0
	global_load_dword v15, v32, s[0:1] nt
	s_add_u32 s0, s0, s6
	s_addc_u32 s1, s1, 0
	global_load_dword v16, v32, s[0:1] nt
	s_add_u32 s0, s0, s6
	s_addc_u32 s1, s1, 0
	global_load_dword v17, v32, s[0:1] nt
	s_add_u32 s0, s0, s6
	s_addc_u32 s1, s1, 0
	global_load_dword v18, v32, s[0:1] nt
	s_add_u32 s0, s0, s6
	s_addc_u32 s1, s1, 0
	global_load_dword v19, v32, s[0:1] nt
	s_add_u32 s0, s0, s6
	s_addc_u32 s1, s1, 0
	global_load_dword v20, v32, s[0:1] nt
	s_add_u32 s0, s0, s6
	s_addc_u32 s1, s1, 0
	global_load_dword v21, v32, s[0:1] nt
	s_add_u32 s0, s0, s6
	s_addc_u32 s1, s1, 0
	global_load_dword v22, v32, s[0:1] nt
	s_add_u32 s0, s0, s6
	s_addc_u32 s1, s1, 0
	global_load_dword v23, v32, s[0:1] nt
	s_add_u32 s0, s0, s6
	s_addc_u32 s1, s1, 0
	global_load_dword v24, v32, s[0:1] nt
	s_add_u32 s0, s0, s6
	s_addc_u32 s1, s1, 0
	global_load_dword v25, v32, s[0:1] nt
	s_add_u32 s0, s0, s6
	s_addc_u32 s1, s1, 0
	global_load_dword v26, v32, s[0:1] nt
	s_add_u32 s0, s0, s6
	s_addc_u32 s1, s1, 0
	global_load_dword v27, v32, s[0:1] nt
	s_add_u32 s0, s0, s6
	s_addc_u32 s1, s1, 0
	global_load_dword v28, v32, s[0:1] nt
	s_add_u32 s0, s0, s6
	s_addc_u32 s1, s1, 0
	global_load_dword v29, v32, s[0:1] nt
	s_add_u32 s0, s0, s6
	s_addc_u32 s1, s1, 0
	global_load_dword v30, v32, s[0:1] nt
	s_add_u32 s0, s0, s6
	s_addc_u32 s1, s1, 0
	global_load_dword v31, v32, s[0:1] nt
	s_cmp_eq_u32 s13, 0
	s_cbranch_scc0 .Ltr_convert
	s_waitcnt vmcnt(28)
	ds_write_b32 v33, v0
	ds_write_b32 v33, v1 offset:264
	ds_write_b32 v33, v2 offset:528
	ds_write_b32 v33, v3 offset:792
	s_waitcnt vmcnt(24)
	ds_write_b32 v33, v4 offset:1056
	ds_write_b32 v33, v5 offset:1320
	ds_write_b32 v33, v6 offset:1584
	ds_write_b32 v33, v7 offset:1848
	s_waitcnt vmcnt(20)
	ds_write_b32 v33, v8 offset:2112
	ds_write_b32 v33, v9 offset:2376
	ds_write_b32 v33, v10 offset:2640
	ds_write_b32 v33, v11 offset:2904
	s_waitcnt vmcnt(16)
	ds_write_b32 v33, v12 offset:3168
	ds_write_b32 v33, v13 offset:3432
	ds_write_b32 v33, v14 offset:3696
	ds_write_b32 v33, v15 offset:3960
	s_waitcnt vmcnt(12)
	ds_write_b32 v33, v16 offset:4224
	ds_write_b32 v33, v17 offset:4488
	ds_write_b32 v33, v18 offset:4752
	ds_write_b32 v33, v19 offset:5016
	s_waitcnt vmcnt(8)
	ds_write_b32 v33, v20 offset:5280
	ds_write_b32 v33, v21 offset:5544
	ds_write_b32 v33, v22 offset:5808
	ds_write_b32 v33, v23 offset:6072
	s_waitcnt vmcnt(4)
	ds_write_b32 v33, v24 offset:6336
	ds_write_b32 v33, v25 offset:6600
	ds_write_b32 v33, v26 offset:6864
	ds_write_b32 v33, v27 offset:7128
	s_waitcnt vmcnt(0)
	ds_write_b32 v33, v28 offset:7392
	ds_write_b32 v33, v29 offset:7656
	ds_write_b32 v33, v30 offset:7920
	ds_write_b32 v33, v31 offset:8184
	s_mov_b32 s13, 1
	s_mov_b64 s[8:9], s[2:3]
	s_branch .Ltr_next
; #define GAS __attribute__((address_space(1)))
; #define LAS __attribute__((address_space(3)))
; #define LDS_WAIT() asm volatile("s_waitcnt lgkmcnt(0)" ::: "memory")
; __device__ __forceinline__ unsigned pk2(float lo, float hi) { return f2bf(lo) | (f2bf(hi) << 16); }
; __device__ __forceinline__ void p0_transpose_item(const float* W, int K, int N, bf16* WT, LAS float* scr, int item, int lane) {
;     ...
;     const int c = lane & 7;
; #pragma unroll
;     for (int j = 0; j < 4; ++j) { const int n = (lane >> 3) + 8 * j; const LAS float* s = scr + (8 * c) * 33 + n;
;         v4u o; o.x = pk2(s[0 * 33], s[1 * 33]); o.y = pk2(s[2 * 33], s[3 * 33]); o.z = pk2(s[4 * 33], s[5 * 33]); o.w = pk2(s[6 * 33], s[7 * 33]);
;         *(GAS v4u*)(WT + (size_t)(n0 + n) * K + k0 + 8 * c) = o; }
;     LDS_WAIT(); asm volatile("" ::: "memory");
; __device__ __forceinline__ void rms_row_to_bf16(const Frame& F, const float* xrow, const float* g, bf16* orow) {
;     const GAS f32x4* xr = (const GAS f32x4*)xrow + F.lane; const GAS f32x4* gr = (const GAS f32x4*)g + F.lane;
;     f32x4 v[8]; float s = 0.f;
; #pragma unroll
;     for (int j = 0; j < 8; ++j) { v[j] = __builtin_nontemporal_load(xr + 64 * j); s += (v[j].x * v[j].x + v[j].y * v[j].y) + (v[j].z * v[j].z + v[j].w * v[j].w); }
;     const float rstd = 1.f / sqrtf(wave_sum(s) * (1.f / D) + EPS);
.Ltr_none:
	s_cmp_eq_u32 s13, 0
	s_cbranch_scc1 .Ltr_done
	s_mov_b32 s13, 2
.Ltr_convert:
	ds_read2_b32 v[40:41], v34 offset1:8
	ds_read2_b32 v[42:43], v34 offset0:33 offset1:41
	ds_read2_b32 v[44:45], v34 offset0:66 offset1:74
	ds_read2_b32 v[46:47], v34 offset0:99 offset1:107
	ds_read2_b32 v[48:49], v34 offset0:132 offset1:140
	ds_read2_b32 v[50:51], v34 offset0:165 offset1:173
	ds_read2_b32 v[52:53], v34 offset0:198 offset1:206
	ds_read2_b32 v[54:55], v34 offset0:231 offset1:239
	ds_read2_b32 v[56:57], v34 offset0:16 offset1:24
	ds_read2_b32 v[58:59], v34 offset0:49 offset1:57
	ds_read2_b32 v[60:61], v34 offset0:82 offset1:90
	ds_read2_b32 v[62:63], v34 offset0:115 offset1:123
	ds_read2_b32 v[64:65], v34 offset0:148 offset1:156
	ds_read2_b32 v[66:67], v34 offset0:181 offset1:189
	ds_read2_b32 v[68:69], v34 offset0:214 offset1:222
	s_waitcnt lgkmcnt(7)
	ds_read2_b32 v[70:71], v34 offset0:247 offset1:255
	v_cvt_pk_bf16_f32 v72, v40, v42
	v_cvt_pk_bf16_f32 v73, v44, v46
	v_cvt_pk_bf16_f32 v74, v48, v50
	v_cvt_pk_bf16_f32 v75, v52, v54
	v_cvt_pk_bf16_f32 v76, v41, v43
	v_cvt_pk_bf16_f32 v77, v45, v47
	v_cvt_pk_bf16_f32 v78, v49, v51
	v_cvt_pk_bf16_f32 v79, v53, v55
	global_store_dwordx4 v35, v[72:75], s[8:9]
	s_add_u32 s8, s8, 0x8000
	s_addc_u32 s9, s9, 0
	global_store_dwordx4 v35, v[76:79], s[8:9]
	s_add_u32 s8, s8, 0x8000
	s_addc_u32 s9, s9, 0
	s_waitcnt lgkmcnt(0)
	v_cvt_pk_bf16_f32 v80, v56, v58
	v_cvt_pk_bf16_f32 v81, v60, v62
	v_cvt_pk_bf16_f32 v82, v64, v66
	v_cvt_pk_bf16_f32 v83, v68, v70
	v_cvt_pk_bf16_f32 v84, v57, v59
	v_cvt_pk_bf16_f32 v85, v61, v63
	v_cvt_pk_bf16_f32 v86, v65, v67
	v_cvt_pk_bf16_f32 v87, v69, v71
	global_store_dwordx4 v35, v[80:83], s[8:9]
	s_add_u32 s8, s8, 0x8000
	s_addc_u32 s9, s9, 0
	global_store_dwordx4 v35, v[84:87], s[8:9]
	s_cmp_eq_u32 s13, 2
	s_cbranch_scc1 .Ltr_done
	s_waitcnt vmcnt(32)
	ds_write_b32 v33, v0
	ds_write_b32 v33, v1 offset:264
	ds_write_b32 v33, v2 offset:528
	ds_write_b32 v33, v3 offset:792
	s_waitcnt vmcnt(28)
	ds_write_b32 v33, v4 offset:1056
	ds_write_b32 v33, v5 offset:1320
	ds_write_b32 v33, v6 offset:1584
	ds_write_b32 v33, v7 offset:1848
	s_waitcnt vmcnt(24)
	ds_write_b32 v33, v8 offset:2112
	ds_write_b32 v33, v9 offset:2376
	ds_write_b32 v33, v10 offset:2640
	ds_write_b32 v33, v11 offset:2904
	s_waitcnt vmcnt(20)
	ds_write_b32 v33, v12 offset:3168
	ds_write_b32 v33, v13 offset:3432
	ds_write_b32 v33, v14 offset:3696
	ds_write_b32 v33, v15 offset:3960
	s_waitcnt vmcnt(16)
	ds_write_b32 v33, v16 offset:4224
	ds_write_b32 v33, v17 offset:4488
	ds_write_b32 v33, v18 offset:4752
	ds_write_b32 v33, v19 offset:5016
	s_waitcnt vmcnt(12)
	ds_write_b32 v33, v20 offset:5280
	ds_write_b32 v33, v21 offset:5544
	ds_write_b32 v33, v22 offset:5808
	ds_write_b32 v33, v23 offset:6072
	s_waitcnt vmcnt(8)
	ds_write_b32 v33, v24 offset:6336
	ds_write_b32 v33, v25 offset:6600
	ds_write_b32 v33, v26 offset:6864
	ds_write_b32 v33, v27 offset:7128
	s_waitcnt vmcnt(4)
	ds_write_b32 v33, v28 offset:7392
	ds_write_b32 v33, v29 offset:7656
	ds_write_b32 v33, v30 offset:7920
	ds_write_b32 v33, v31 offset:8184
	s_mov_b64 s[8:9], s[2:3]
	s_branch .Ltr_next
.Ltr_done:
.LBB0_53:
	s_cmpk_gt_i32 s74, 0x3fff
	s_cbranch_scc1 .LBB0_56
	v_readlane_b32 s36, v234, 5
	v_readlane_b32 s37, v234, 6
	v_readlane_b32 s38, v234, 7
	v_readlane_b32 s39, v234, 8
	s_mov_b64 s[0:1], s[36:37]
	v_lshlrev_b32_e32 v0, 4, v156
	v_mov_b32_e32 v1, 0
	s_mov_b64 s[2:3], s[38:39]
	v_lshl_add_u64 v[12:13], s[0:1], 0, v[0:1]
	v_lshl_add_u64 v[14:15], s[2:3], 0, v[0:1]
	v_mbcnt_lo_u32_b32 v0, -1, 0
	v_mbcnt_hi_u32_b32 v0, -1, v0
	v_and_b32_e32 v2, 64, v0
	v_add_u32_e32 v2, 64, v2
	v_xor_b32_e32 v3, 1, v0
	v_cmp_lt_i32_e32 vcc, v3, v2
	s_mov_b64 s[0:1], 0x1000
	v_lshl_add_u64 v[18:19], v[14:15], 0, s[0:1]
	v_cndmask_b32_e32 v3, v0, v3, vcc
	v_lshlrev_b32_e32 v29, 2, v3
	v_xor_b32_e32 v3, 2, v0
	v_cmp_lt_i32_e32 vcc, v3, v2
	s_mov_b64 s[0:1], 0x1400
	v_lshl_add_u64 v[20:21], v[14:15], 0, s[0:1]
	v_cndmask_b32_e32 v3, v0, v3, vcc
	v_lshlrev_b32_e32 v30, 2, v3
	v_xor_b32_e32 v3, 4, v0
	v_cmp_lt_i32_e32 vcc, v3, v2
	s_mov_b64 s[0:1], 0x1800
	v_lshl_add_u64 v[22:23], v[14:15], 0, s[0:1]
	v_cndmask_b32_e32 v3, v0, v3, vcc
	v_lshlrev_b32_e32 v31, 2, v3
	v_xor_b32_e32 v3, 8, v0
	v_cmp_lt_i32_e32 vcc, v3, v2
	s_mov_b64 s[0:1], 0x1c00
	s_ashr_i32 s75, s74, 31
	v_cndmask_b32_e32 v3, v0, v3, vcc
	v_lshlrev_b32_e32 v32, 2, v3
	v_xor_b32_e32 v3, 16, v0
	v_cmp_lt_i32_e32 vcc, v3, v2
	s_ashr_i32 s79, s78, 31
	v_lshl_add_u64 v[24:25], v[14:15], 0, s[0:1]
	v_cndmask_b32_e32 v3, v0, v3, vcc
	v_lshlrev_b32_e32 v33, 2, v3
	v_xor_b32_e32 v3, 32, v0
	v_cmp_lt_i32_e32 vcc, v3, v2
	s_lshl_b64 s[2:3], s[74:75], 13
	s_lshl_b64 s[6:7], s[78:79], 13
	v_cndmask_b32_e32 v0, v0, v3, vcc
	v_lshlrev_b32_e32 v34, 2, v0
	v_lshlrev_b32_e32 v0, 3, v156
	v_lshl_add_u64 v[16:17], s[86:87], 0, v[0:1]
	s_movk_i32 s8, 0x1000
	v_mov_b32_e32 v35, 0x358637bd
	s_mov_b32 s9, 0xf800000
	v_mov_b32_e32 v36, 0x260
	s_movk_i32 s10, 0x7fff
	v_mov_b32_e32 v37, 1
	s_mov_b32 s11, s74
	v_readlane_b32 s40, v234, 9
	v_readlane_b32 s41, v234, 10
	v_readlane_b32 s42, v234, 11
	v_readlane_b32 s43, v234, 12
	v_readlane_b32 s44, v234, 13
	v_readlane_b32 s45, v234, 14
	v_readlane_b32 s46, v234, 15
	v_readlane_b32 s47, v234, 16
	v_readlane_b32 s48, v234, 17
	v_readlane_b32 s49, v234, 18
	v_readlane_b32 s50, v234, 19
	v_readlane_b32 s51, v234, 20

; #define GAS __attribute__((address_space(1)))
; #define LAS __attribute__((address_space(3)))
; #define LDS_WAIT() asm volatile("s_waitcnt lgkmcnt(0)" ::: "memory")
; __device__ __forceinline__ unsigned pk2(float lo, float hi) { return f2bf(lo) | (f2bf(hi) << 16); }
; __device__ __forceinline__ void p0_transpose_item(const float* W, int K, int N, bf16* WT, LAS float* scr, int item, int lane) {
;     const int nblk = N / 32, kb = item / nblk, nb = item % nblk, k0 = 64 * kb, n0 = 32 * nb;
; #pragma unroll 8
;     for (int i = 0; i < 32; ++i) { const int kk = 2 * i + (lane >> 5); scr[kk * 33 + (lane & 31)] = __builtin_nontemporal_load(W + (size_t)(k0 + kk) * N + n0 + (lane & 31)); }
;     LDS_WAIT(); asm volatile("" ::: "memory");
;     const int c = lane & 7;
; #pragma unroll
;     for (int j = 0; j < 4; ++j) { const int n = (lane >> 3) + 8 * j; const LAS float* s = scr + (8 * c) * 33 + n;
;         v4u o; o.x = pk2(s[0 * 33], s[1 * 33]); o.y = pk2(s[2 * 33], s[3 * 33]); o.z = pk2(s[4 * 33], s[5 * 33]); o.w = pk2(s[6 * 33], s[7 * 33]);
;         *(GAS v4u*)(WT + (size_t)(n0 + n) * K + k0 + 8 * c) = o; }
;     LDS_WAIT(); asm volatile("" ::: "memory");
; }
; __device__ __forceinline__ void transpose_all(const Frame& F, const float* W, int K, int N, bf16* WT) {
;     LAS float* scr = (LAS float*)(F.lds + F.wave * 16384);
;     const int gw = F.vcu * NWAVES + F.wave, NGW = F.G * NWAVES, nitems = (K / 64) * (N / 32);
;     for (int it = gw; it < nitems; it += NGW) p0_transpose_item(W, K, N, WT, scr, it, F.lane);
; __global__ void __launch_bounds__(NWAVES * 64, 2) mega(Args args) {
;     ...
;         transpose_all(F, args.in[15], FF, D, (bf16*)(ws + WS_WDN));
.LBB0_609:
	s_cmp_lt_i32 s90, 5
	s_cselect_b64 s[2:3], -1, 0
	s_and_b64 s[4:5], s[2:3], s[0:1]
	s_andn2_b64 vcc, exec, s[4:5]
	s_cbranch_vccnz .LBB0_663
	s_lshl_b32 s0, s93, 3
	s_add_i32 s6, s0, s92
	s_lshl_b32 s8, s92, 14
	v_lshrrev_b32_e32 v36, 5, v156
	v_and_b32_e32 v37, 31, v156
	v_lshlrev_b32_e32 v37, 2, v37
	s_movk_i32 s7, 0x84
	v_mad_u32_u24 v33, v36, s7, v37
	v_add_u32_e32 v33, s8, v33
	v_and_b32_e32 v38, 7, v156
	v_lshrrev_b32_e32 v39, 3, v156
	s_movk_i32 s7, 0x420
	v_lshlrev_b32_e32 v34, 2, v39
	v_mad_u32_u24 v34, v38, s7, v34
	v_add_u32_e32 v34, s8, v34
	v_lshlrev_b32_e32 v35, 14, v39
	v_lshl_add_u32 v35, v38, 4, v35
	v_readlane_b32 s14, v234, 35
	v_readlane_b32 s15, v234, 36
	s_mov_b32 s17, s6
	s_movk_i32 s7, 0x2000
	v_mad_u32_u24 v32, v36, s7, v37
	s_add_u32 s10, s88, 0xa000000
	s_addc_u32 s11, s89, 0
	s_mov_b32 s13, 0
	s_nop 3
	s_branch .Ltd_chk
.Ltd_next:
	s_add_u32 s17, s17, s78
.Ltd_chk:
	s_cmp_lt_u32 s17, 0x2000
	s_cbranch_scc0 .Ltd_none
	s_lshr_b32 s7, s17, 6
	s_and_b32 s12, s17, 63
	s_lshl_b32 s6, s12, 19
	s_lshl_b32 s0, s7, 7
	s_add_u32 s6, s6, s0
	s_add_u32 s2, s10, s6
	s_addc_u32 s3, s11, 0
	s_lshl_b32 s0, s7, 19
	s_lshl_b32 s1, s12, 7
	s_add_u32 s0, s0, s1
	s_add_u32 s0, s14, s0
	s_addc_u32 s1, s15, 0
	s_movk_i32 s6, 0x4000
	global_load_dword v0, v32, s[0:1] nt
	s_add_u32 s0, s0, s6
	s_addc_u32 s1, s1, 0
	global_load_dword v1, v32, s[0:1] nt
	s_add_u32 s0, s0, s6
	s_addc_u32 s1, s1, 0
	global_load_dword v2, v32, s[0:1] nt
	s_add_u32 s0, s0, s6
	s_addc_u32 s1, s1, 0
	global_load_dword v3, v32, s[0:1] nt
	s_add_u32 s0, s0, s6
	s_addc_u32 s1, s1, 0
	global_load_dword v4, v32, s[0:1] nt
	s_add_u32 s0, s0, s6
	s_addc_u32 s1, s1, 0
	global_load_dword v5, v32, s[0:1] nt
	s_add_u32 s0, s0, s6
	s_addc_u32 s1, s1, 0
	global_load_dword v6, v32, s[0:1] nt
	s_add_u32 s0, s0, s6
	s_addc_u32 s1, s1, 0
	global_load_dword v7, v32, s[0:1] nt
	s_add_u32 s0, s0, s6
	s_addc_u32 s1, s1, 0
	global_load_dword v8, v32, s[0:1] nt
	s_add_u32 s0, s0, s6
	s_addc_u32 s1, s1, 0
	global_load_dword v9, v32, s[0:1] nt
	s_add_u32 s0, s0, s6
	s_addc_u32 s1, s1, 0
	global_load_dword v10, v32, s[0:1] nt
	s_add_u32 s0, s0, s6
	s_addc_u32 s1, s1, 0
	global_load_dword v11, v32, s[0:1] nt
	s_add_u32 s0, s0, s6
	s_addc_u32 s1, s1, 0
	global_load_dword v12, v32, s[0:1] nt
	s_add_u32 s0, s0, s6
	s_addc_u32 s1, s1, 0
	global_load_dword v13, v32, s[0:1] nt
	s_add_u32 s0, s0, s6
	s_addc_u32 s1, s1, 0
	global_load_dword v14, v32, s[0:1] nt
	s_add_u32 s0, s0, s6
	s_addc_u32 s1, s1, 0
	global_load_dword v15, v32, s[0:1] nt
	s_add_u32 s0, s0, s6
	s_addc_u32 s1, s1, 0
	global_load_dword v16, v32, s[0:1] nt
	s_add_u32 s0, s0, s6
	s_addc_u32 s1, s1, 0
	global_load_dword v17, v32, s[0:1] nt
	s_add_u32 s0, s0, s6
	s_addc_u32 s1, s1, 0
	global_load_dword v18, v32, s[0:1] nt
	s_add_u32 s0, s0, s6
	s_addc_u32 s1, s1, 0
	global_load_dword v19, v32, s[0:1] nt
	s_add_u32 s0, s0, s6
	s_addc_u32 s1, s1, 0
	global_load_dword v20, v32, s[0:1] nt
	s_add_u32 s0, s0, s6
	s_addc_u32 s1, s1, 0
	global_load_dword v21, v32, s[0:1] nt
	s_add_u32 s0, s0, s6
	s_addc_u32 s1, s1, 0
	global_load_dword v22, v32, s[0:1] nt
	s_add_u32 s0, s0, s6
	s_addc_u32 s1, s1, 0
	global_load_dword v23, v32, s[0:1] nt
	s_add_u32 s0, s0, s6
	s_addc_u32 s1, s1, 0
	global_load_dword v24, v32, s[0:1] nt
	s_add_u32 s0, s0, s6
	s_addc_u32 s1, s1, 0
	global_load_dword v25, v32, s[0:1] nt
	s_add_u32 s0, s0, s6
	s_addc_u32 s1, s1, 0
	global_load_dword v26, v32, s[0:1] nt
	s_add_u32 s0, s0, s6
	s_addc_u32 s1, s1, 0
	global_load_dword v27, v32, s[0:1] nt
	s_add_u32 s0, s0, s6
	s_addc_u32 s1, s1, 0
	global_load_dword v28, v32, s[0:1] nt
	s_add_u32 s0, s0, s6
	s_addc_u32 s1, s1, 0
	global_load_dword v29, v32, s[0:1] nt
	s_add_u32 s0, s0, s6
	s_addc_u32 s1, s1, 0
	global_load_dword v30, v32, s[0:1] nt
	s_add_u32 s0, s0, s6
	s_addc_u32 s1, s1, 0
	global_load_dword v31, v32, s[0:1] nt
	s_cmp_eq_u32 s13, 0
	s_cbranch_scc0 .Ltd_convert
	s_waitcnt vmcnt(28)
	ds_write_b32 v33, v0
	ds_write_b32 v33, v1 offset:264
	ds_write_b32 v33, v2 offset:528
	ds_write_b32 v33, v3 offset:792
	s_waitcnt vmcnt(24)
	ds_write_b32 v33, v4 offset:1056
	ds_write_b32 v33, v5 offset:1320
	ds_write_b32 v33, v6 offset:1584
	ds_write_b32 v33, v7 offset:1848
	s_waitcnt vmcnt(20)
	ds_write_b32 v33, v8 offset:2112
	ds_write_b32 v33, v9 offset:2376
	ds_write_b32 v33, v10 offset:2640
	ds_write_b32 v33, v11 offset:2904
	s_waitcnt vmcnt(16)
	ds_write_b32 v33, v12 offset:3168
	ds_write_b32 v33, v13 offset:3432
	ds_write_b32 v33, v14 offset:3696
	ds_write_b32 v33, v15 offset:3960
	s_waitcnt vmcnt(12)
	ds_write_b32 v33, v16 offset:4224
	ds_write_b32 v33, v17 offset:4488
	ds_write_b32 v33, v18 offset:4752
	ds_write_b32 v33, v19 offset:5016
	s_waitcnt vmcnt(8)
	ds_write_b32 v33, v20 offset:5280
	ds_write_b32 v33, v21 offset:5544
	ds_write_b32 v33, v22 offset:5808
	ds_write_b32 v33, v23 offset:6072
	s_waitcnt vmcnt(4)
	ds_write_b32 v33, v24 offset:6336
	ds_write_b32 v33, v25 offset:6600
	ds_write_b32 v33, v26 offset:6864
	ds_write_b32 v33, v27 offset:7128
	s_waitcnt vmcnt(0)
	ds_write_b32 v33, v28 offset:7392
	ds_write_b32 v33, v29 offset:7656
	ds_write_b32 v33, v30 offset:7920
	ds_write_b32 v33, v31 offset:8184
	s_mov_b32 s13, 1
	s_mov_b64 s[8:9], s[2:3]
	s_branch .Ltd_next

; #define GAS __attribute__((address_space(1)))
; #define LAS __attribute__((address_space(3)))
; #define LDS_WAIT() asm volatile("s_waitcnt lgkmcnt(0)" ::: "memory")
; __device__ __forceinline__ unsigned pk2(float lo, float hi) { return f2bf(lo) | (f2bf(hi) << 16); }
; template <class Epi, class Sched, bool ALIGN_EPI = false, bool SP2 = false>
; __device__ __forceinline__ void gemm_phase(PG8_LAS unsigned char* lds, const Gemm g, const Sched& S, const Epi& E) {
;     const int tid = threadIdx.x, wid = __builtin_amdgcn_readfirstlane(tid >> 6), lane = tid & 63, wr = wid >> 2, wc = wid & 3, fr = lane & 15, fq = lane >> 4;
;     const int K = g.K, nt = K / BK;
;     unsigned voffA[2], voffB[2];
; #pragma unroll
;     for (int i = 0; i < 2; ++i) { int R, C; stage_rc(tid * 16 + i * 8192, R, C); const int Rb = Epi::PERM ? ((R & ~31) + perm32(R & 31)) : R;
;         voffA[i] = (unsigned)(R * g.lda + C) * 2u; voffB[i] = (unsigned)(Rb * K + C) * 2u; }
;     const size_t kstep = (size_t)(BK * 2);
;     const size_t hstepA = (size_t)HALF * g.lda * 2, hstepB = (size_t)HALF * K * 2;
;     const size_t tstepA = 2 * hstepA, tstepB = 2 * hstepB;
;     const unsigned ldsw = (unsigned)wid * 1024u;
;     const int aoff = lds_byte(wr * 64 + fr, fq * 8), boff = lds_byte(wc * 32 + fr, fq * 8);
; __device__ __forceinline__ void p0_transpose_item(const float* W, int K, int N, bf16* WT, LAS float* scr, int item, int lane) {
;     ...
;     const int c = lane & 7;
; #pragma unroll
;     for (int j = 0; j < 4; ++j) { const int n = (lane >> 3) + 8 * j; const LAS float* s = scr + (8 * c) * 33 + n;
;         v4u o; o.x = pk2(s[0 * 33], s[1 * 33]); o.y = pk2(s[2 * 33], s[3 * 33]); o.z = pk2(s[4 * 33], s[5 * 33]); o.w = pk2(s[6 * 33], s[7 * 33]);
;         *(GAS v4u*)(WT + (size_t)(n0 + n) * K + k0 + 8 * c) = o; }
;     LDS_WAIT(); asm volatile("" ::: "memory");
.Ltd_convert:
	ds_read2_b32 v[40:41], v34 offset1:8
	ds_read2_b32 v[42:43], v34 offset0:33 offset1:41
	ds_read2_b32 v[44:45], v34 offset0:66 offset1:74
	ds_read2_b32 v[46:47], v34 offset0:99 offset1:107
	ds_read2_b32 v[48:49], v34 offset0:132 offset1:140
	ds_read2_b32 v[50:51], v34 offset0:165 offset1:173
	ds_read2_b32 v[52:53], v34 offset0:198 offset1:206
	ds_read2_b32 v[54:55], v34 offset0:231 offset1:239
	ds_read2_b32 v[56:57], v34 offset0:16 offset1:24
	ds_read2_b32 v[58:59], v34 offset0:49 offset1:57
	ds_read2_b32 v[60:61], v34 offset0:82 offset1:90
	ds_read2_b32 v[62:63], v34 offset0:115 offset1:123
	ds_read2_b32 v[64:65], v34 offset0:148 offset1:156
	ds_read2_b32 v[66:67], v34 offset0:181 offset1:189
	ds_read2_b32 v[68:69], v34 offset0:214 offset1:222
	s_waitcnt lgkmcnt(7)
	ds_read2_b32 v[70:71], v34 offset0:247 offset1:255
	v_cvt_pk_bf16_f32 v72, v40, v42
	v_cvt_pk_bf16_f32 v73, v44, v46
	v_cvt_pk_bf16_f32 v74, v48, v50
	v_cvt_pk_bf16_f32 v75, v52, v54
	v_cvt_pk_bf16_f32 v76, v41, v43
	v_cvt_pk_bf16_f32 v77, v45, v47
	v_cvt_pk_bf16_f32 v78, v49, v51
	v_cvt_pk_bf16_f32 v79, v53, v55
	global_store_dwordx4 v35, v[72:75], s[8:9]
	s_add_u32 s8, s8, 0x20000
	s_addc_u32 s9, s9, 0
	global_store_dwordx4 v35, v[76:79], s[8:9]
	s_add_u32 s8, s8, 0x20000
	s_addc_u32 s9, s9, 0
	s_waitcnt lgkmcnt(0)
	v_cvt_pk_bf16_f32 v80, v56, v58
	v_cvt_pk_bf16_f32 v81, v60, v62
	v_cvt_pk_bf16_f32 v82, v64, v66
	v_cvt_pk_bf16_f32 v83, v68, v70
	v_cvt_pk_bf16_f32 v84, v57, v59
	v_cvt_pk_bf16_f32 v85, v61, v63
	v_cvt_pk_bf16_f32 v86, v65, v67
	v_cvt_pk_bf16_f32 v87, v69, v71
	global_store_dwordx4 v35, v[80:83], s[8:9]
	s_add_u32 s8, s8, 0x20000
	s_addc_u32 s9, s9, 0
	global_store_dwordx4 v35, v[84:87], s[8:9]
	s_cmp_eq_u32 s13, 2
	s_cbranch_scc1 .Ltd_done
	s_waitcnt vmcnt(32)
	ds_write_b32 v33, v0
	ds_write_b32 v33, v1 offset:264
	ds_write_b32 v33, v2 offset:528
	ds_write_b32 v33, v3 offset:792
	s_waitcnt vmcnt(28)
	ds_write_b32 v33, v4 offset:1056
	ds_write_b32 v33, v5 offset:1320
	ds_write_b32 v33, v6 offset:1584
	ds_write_b32 v33, v7 offset:1848
	s_waitcnt vmcnt(24)
	ds_write_b32 v33, v8 offset:2112
	ds_write_b32 v33, v9 offset:2376
	ds_write_b32 v33, v10 offset:2640
	ds_write_b32 v33, v11 offset:2904
	s_waitcnt vmcnt(20)
	ds_write_b32 v33, v12 offset:3168
	ds_write_b32 v33, v13 offset:3432
	ds_write_b32 v33, v14 offset:3696
	ds_write_b32 v33, v15 offset:3960
	s_waitcnt vmcnt(16)
	ds_write_b32 v33, v16 offset:4224
	ds_write_b32 v33, v17 offset:4488
	ds_write_b32 v33, v18 offset:4752
	ds_write_b32 v33, v19 offset:5016
	s_waitcnt vmcnt(12)
	ds_write_b32 v33, v20 offset:5280
	ds_write_b32 v33, v21 offset:5544
	ds_write_b32 v33, v22 offset:5808
	ds_write_b32 v33, v23 offset:6072
	s_waitcnt vmcnt(8)
	ds_write_b32 v33, v24 offset:6336
	ds_write_b32 v33, v25 offset:6600
	ds_write_b32 v33, v26 offset:6864
	ds_write_b32 v33, v27 offset:7128
	s_waitcnt vmcnt(4)
	ds_write_b32 v33, v28 offset:7392
	ds_write_b32 v33, v29 offset:7656
	ds_write_b32 v33, v30 offset:7920
	ds_write_b32 v33, v31 offset:8184
	s_mov_b64 s[8:9], s[2:3]
	s_branch .Ltd_next
.Ltd_done:
.LBB0_615:
	v_lshrrev_b32_e32 v2, 5, v157
	v_lshrrev_b32_e32 v4, 1, v157
	v_and_b32_e32 v2, 4, v2
	v_bfe_u32 v3, v157, 2, 2
	v_and_b32_e32 v153, 24, v4
	v_lshlrev_b32_e32 v0, 4, v157
	v_and_b32_e32 v1, 32, v157
	v_bfe_u32 v152, v157, 2, 4
	v_or3_b32 v2, v2, v3, v153
	v_lshrrev_b32_e32 v3, 3, v157
	s_movk_i32 s0, 0x70
	v_bitop3_b32 v150, v0, v1, 48 bitop3:0x6c
	v_and_b32_e32 v151, 64, v157
	v_and_or_b32 v4, v3, s0, v152
	s_movk_i32 s0, 0x60
	v_add_u32_e32 v154, 0x2000, v0
	v_or_b32_e32 v1, v150, v151
	v_and_or_b32 v3, v3, s0, v2
	v_lshrrev_b32_e32 v0, 7, v154
	s_movk_i32 s0, 0xf0
	v_lshl_or_b32 v130, v3, 12, v1
	v_and_or_b32 v3, v0, s0, v152
	s_movk_i32 s0, 0xe0
	s_add_u32 s6, s88, 0x6000000
	v_and_or_b32 v0, v0, s0, v2
	s_addc_u32 s7, s89, 0
	v_lshl_or_b32 v128, v4, 13, v1
	v_lshl_or_b32 v132, v3, 13, v1
	v_lshl_or_b32 v134, v0, 12, v1
	v_lshlrev_b32_e32 v0, 6, v157
	v_lshlrev_b32_e32 v1, 2, v157
	v_readlane_b32 s0, v234, 2
	v_lshlrev_b32_e32 v158, 1, v153
	v_and_b32_e32 v0, 0x3c0, v0
	v_and_b32_e32 v1, 32, v1
	s_cmpk_lt_i32 s0, 0x200
	v_readfirstlane_b32 s16, v157
	v_and_b32_e32 v155, 15, v157
	s_cselect_b64 s[8:9], -1, 0
	s_cmpk_gt_i32 s0, 0x1ff
	v_bitop3_b32 v159, v158, v1, v0 bitop3:0x36
	s_waitcnt vmcnt(0)
	s_barrier
	s_cbranch_scc1 .LBB0_639
	v_readlane_b32 s1, v234, 2
	s_ashr_i32 s50, s1, 31
	s_lshr_b32 s0, s50, 29
	s_add_i32 s2, s1, s0
	s_and_b32 s0, s2, -8
	s_sub_i32 s10, s1, s0
	s_cmp_gt_i32 s10, -1
	s_cbranch_scc0 .LBB0_618
	s_lshl_b32 s3, s10, 6
	s_cbranch_execz .LBB0_619
	s_branch .LBB0_620
